# adaLN item: first wait tightened to vmcnt(31) so the 6-bit counter cannot overflow (otherwise as the previous adaLN version)
# speedup vs baseline: 1.0010x; 1.0010x over previous
.LBB0_73:
	v_mov_b32_e32 v0, v188
	v_lshlrev_b32_e32 v21, 2, v0
	s_mov_b64 s[10:11], s[42:43]
	global_load_dword v94, v21, s[10:11]
	global_load_dword v95, v21, s[10:11] offset:2048
	s_add_u32 s10, s10, 0x1000
	s_addc_u32 s11, s11, 0
	global_load_dword v96, v21, s[10:11]
	global_load_dword v97, v21, s[10:11] offset:2048
	s_add_u32 s10, s10, 0x1000
	s_addc_u32 s11, s11, 0
	global_load_dword v98, v21, s[10:11]
	global_load_dword v99, v21, s[10:11] offset:2048
	s_add_u32 s10, s10, 0x1000
	s_addc_u32 s11, s11, 0
	global_load_dword v100, v21, s[10:11]
	global_load_dword v101, v21, s[10:11] offset:2048
	global_load_dword v102, v21, s[46:47]
	global_load_dword v103, v21, s[46:47] offset:2048
	v_and_b32_e32 v1, 31, v0
	v_lshrrev_b32_e32 v10, 5, v0
	v_add_u32_e32 v2, s96, v1
	v_lshlrev_b32_e32 v2, 2, v2
	v_mul_u32_u24_e32 v3, 0x180000, v10
	v_add_u32_e32 v3, v3, v2
	s_sub_u32 s8, s26, 0x2a000
	s_subb_u32 s9, s27, 0
	global_load_dword v132, v3, s[8:9]
	s_add_u32 s8, s8, 0x6000
	s_addc_u32 s9, s9, 0
	global_load_dword v133, v3, s[8:9]
	s_add_u32 s8, s8, 0x6000
	s_addc_u32 s9, s9, 0
	global_load_dword v134, v3, s[8:9]
	s_add_u32 s8, s8, 0x6000
	s_addc_u32 s9, s9, 0
	global_load_dword v135, v3, s[8:9]
	s_add_u32 s8, s8, 0x6000
	s_addc_u32 s9, s9, 0
	global_load_dword v136, v3, s[8:9]
	s_add_u32 s8, s8, 0x6000
	s_addc_u32 s9, s9, 0
	global_load_dword v137, v3, s[8:9]
	s_add_u32 s8, s8, 0x6000
	s_addc_u32 s9, s9, 0
	global_load_dword v138, v3, s[8:9]
	s_add_u32 s8, s8, 0x6000
	s_addc_u32 s9, s9, 0
	global_load_dword v139, v3, s[8:9]
	s_add_u32 s8, s8, 0x6000
	s_addc_u32 s9, s9, 0
	global_load_dword v140, v3, s[8:9]
	s_add_u32 s8, s8, 0x6000
	s_addc_u32 s9, s9, 0
	global_load_dword v141, v3, s[8:9]
	s_add_u32 s8, s8, 0x6000
	s_addc_u32 s9, s9, 0
	global_load_dword v142, v3, s[8:9]
	s_add_u32 s8, s8, 0x6000
	s_addc_u32 s9, s9, 0
	global_load_dword v143, v3, s[8:9]
	s_add_u32 s8, s8, 0x6000
	s_addc_u32 s9, s9, 0
	global_load_dword v144, v3, s[8:9]
	s_add_u32 s8, s8, 0x6000
	s_addc_u32 s9, s9, 0
	global_load_dword v145, v3, s[8:9]
	s_add_u32 s8, s8, 0x6000
	s_addc_u32 s9, s9, 0
	global_load_dword v146, v3, s[8:9]
	s_add_u32 s8, s8, 0x6000
	s_addc_u32 s9, s9, 0
	global_load_dword v147, v3, s[8:9]
	s_add_u32 s8, s8, 0x6000
	s_addc_u32 s9, s9, 0
	global_load_dword v148, v3, s[8:9]
	s_add_u32 s8, s8, 0x6000
	s_addc_u32 s9, s9, 0
	global_load_dword v149, v3, s[8:9]
	s_add_u32 s8, s8, 0x6000
	s_addc_u32 s9, s9, 0
	global_load_dword v150, v3, s[8:9]
	s_add_u32 s8, s8, 0x6000
	s_addc_u32 s9, s9, 0
	global_load_dword v151, v3, s[8:9]
	s_add_u32 s8, s8, 0x6000
	s_addc_u32 s9, s9, 0
	global_load_dword v152, v3, s[8:9]
	s_add_u32 s8, s8, 0x6000
	s_addc_u32 s9, s9, 0
	global_load_dword v153, v3, s[8:9]
	s_add_u32 s8, s8, 0x6000
	s_addc_u32 s9, s9, 0
	global_load_dword v154, v3, s[8:9]
	s_add_u32 s8, s8, 0x6000
	s_addc_u32 s9, s9, 0
	global_load_dword v155, v3, s[8:9]
	s_add_u32 s8, s8, 0x6000
	s_addc_u32 s9, s9, 0
	global_load_dword v156, v3, s[8:9]
	s_add_u32 s8, s8, 0x6000
	s_addc_u32 s9, s9, 0
	global_load_dword v157, v3, s[8:9]
	s_add_u32 s8, s8, 0x6000
	s_addc_u32 s9, s9, 0
	global_load_dword v158, v3, s[8:9]
	s_add_u32 s8, s8, 0x6000
	s_addc_u32 s9, s9, 0
	global_load_dword v159, v3, s[8:9]
	s_add_u32 s8, s8, 0x6000
	s_addc_u32 s9, s9, 0
	global_load_dword v160, v3, s[8:9]
	s_add_u32 s8, s8, 0x6000
	s_addc_u32 s9, s9, 0
	global_load_dword v161, v3, s[8:9]
	s_add_u32 s8, s8, 0x6000
	s_addc_u32 s9, s9, 0
	global_load_dword v162, v3, s[8:9]
	s_add_u32 s8, s8, 0x6000
	s_addc_u32 s9, s9, 0
	global_load_dword v163, v3, s[8:9]
	s_add_u32 s8, s8, 0x6000
	s_addc_u32 s9, s9, 0
	s_waitcnt vmcnt(31)
	v_mul_f32_e32 v104, 0xbfb8aa3b, v94
	v_mul_f32_e32 v105, 0xbfb8aa3b, v95
	v_mul_f32_e32 v106, 0xbfb8aa3b, v96
	v_mul_f32_e32 v107, 0xbfb8aa3b, v97
	v_mul_f32_e32 v108, 0xbfb8aa3b, v98
	v_mul_f32_e32 v109, 0xbfb8aa3b, v99
	v_mul_f32_e32 v110, 0xbfb8aa3b, v100
	v_mul_f32_e32 v111, 0xbfb8aa3b, v101
	v_mul_f32_e32 v112, 0xbfb8aa3b, v102
	v_mul_f32_e32 v113, 0xbfb8aa3b, v103
	v_exp_f32_e32 v104, v104
	v_exp_f32_e32 v105, v105
	v_exp_f32_e32 v106, v106
	v_exp_f32_e32 v107, v107
	v_exp_f32_e32 v108, v108
	v_exp_f32_e32 v109, v109
	v_exp_f32_e32 v110, v110
	v_exp_f32_e32 v111, v111
	v_exp_f32_e32 v112, v112
	v_exp_f32_e32 v113, v113
	v_add_f32_e32 v104, 1.0, v104
	v_add_f32_e32 v105, 1.0, v105
	v_add_f32_e32 v106, 1.0, v106
	v_add_f32_e32 v107, 1.0, v107
	v_add_f32_e32 v108, 1.0, v108
	v_add_f32_e32 v109, 1.0, v109
	v_add_f32_e32 v110, 1.0, v110
	v_add_f32_e32 v111, 1.0, v111
	v_add_f32_e32 v112, 1.0, v112
	v_add_f32_e32 v113, 1.0, v113
	v_rcp_f32_e32 v104, v104
	v_rcp_f32_e32 v105, v105
	v_rcp_f32_e32 v106, v106
	v_rcp_f32_e32 v107, v107
	v_rcp_f32_e32 v108, v108
	v_rcp_f32_e32 v109, v109
	v_rcp_f32_e32 v110, v110
	v_rcp_f32_e32 v111, v111
	v_rcp_f32_e32 v112, v112
	v_rcp_f32_e32 v113, v113
	v_mul_f32_e32 v94, v94, v104
	v_mul_f32_e32 v95, v95, v105
	v_mul_f32_e32 v96, v96, v106
	v_mul_f32_e32 v97, v97, v107
	v_mul_f32_e32 v98, v98, v108
	v_mul_f32_e32 v99, v99, v109
	v_mul_f32_e32 v100, v100, v110
	v_mul_f32_e32 v101, v101, v111
	v_mul_f32_e32 v102, v102, v112
	v_mul_f32_e32 v103, v103, v113
	ds_write_b32 v21, v94
	ds_write_b32 v21, v95 offset:2048
	ds_write_b32 v21, v96 offset:4096
	ds_write_b32 v21, v97 offset:6144
	ds_write_b32 v21, v98 offset:8192
	ds_write_b32 v21, v99 offset:10240
	ds_write_b32 v21, v100 offset:12288
	ds_write_b32 v21, v101 offset:14336
	ds_write_b32 v21, v102 offset:16384
	ds_write_b32 v21, v103 offset:18432
	global_load_dword v164, v3, s[8:9]
	s_add_u32 s8, s8, 0x6000
	s_addc_u32 s9, s9, 0
	global_load_dword v165, v3, s[8:9]
	s_add_u32 s8, s8, 0x6000
	s_addc_u32 s9, s9, 0
	global_load_dword v166, v3, s[8:9]
	s_add_u32 s8, s8, 0x6000
	s_addc_u32 s9, s9, 0
	global_load_dword v167, v3, s[8:9]
	s_add_u32 s8, s8, 0x6000
	s_addc_u32 s9, s9, 0
	global_load_dword v168, v3, s[8:9]
	s_add_u32 s8, s8, 0x6000
	s_addc_u32 s9, s9, 0
	global_load_dword v169, v3, s[8:9]
	s_add_u32 s8, s8, 0x6000
	s_addc_u32 s9, s9, 0
	global_load_dword v170, v3, s[8:9]
	s_add_u32 s8, s8, 0x6000
	s_addc_u32 s9, s9, 0
	global_load_dword v171, v3, s[8:9]
	s_add_u32 s8, s8, 0x6000
	s_addc_u32 s9, s9, 0
	global_load_dword v172, v3, s[8:9]
	s_add_u32 s8, s8, 0x6000
	s_addc_u32 s9, s9, 0
	global_load_dword v173, v3, s[8:9]
	s_add_u32 s8, s8, 0x6000
	s_addc_u32 s9, s9, 0
	global_load_dword v174, v3, s[8:9]
	s_add_u32 s8, s8, 0x6000
	s_addc_u32 s9, s9, 0
	global_load_dword v175, v3, s[8:9]
	s_add_u32 s8, s8, 0x6000
	s_addc_u32 s9, s9, 0
	global_load_dword v176, v3, s[8:9]
	s_add_u32 s8, s8, 0x6000
	s_addc_u32 s9, s9, 0
	global_load_dword v177, v3, s[8:9]
	s_add_u32 s8, s8, 0x6000
	s_addc_u32 s9, s9, 0
	global_load_dword v178, v3, s[8:9]
	s_add_u32 s8, s8, 0x6000
	s_addc_u32 s9, s9, 0
	global_load_dword v179, v3, s[8:9]
	s_add_u32 s8, s8, 0x6000
	s_addc_u32 s9, s9, 0
	global_load_dword v180, v3, s[8:9]
	s_add_u32 s8, s8, 0x6000
	s_addc_u32 s9, s9, 0
	global_load_dword v181, v3, s[8:9]
	s_add_u32 s8, s8, 0x6000
	s_addc_u32 s9, s9, 0
	global_load_dword v182, v3, s[8:9]
	s_add_u32 s8, s8, 0x6000
	s_addc_u32 s9, s9, 0
	global_load_dword v183, v3, s[8:9]
	s_add_u32 s8, s8, 0x6000
	s_addc_u32 s9, s9, 0
	global_load_dword v184, v3, s[8:9]
	s_add_u32 s8, s8, 0x6000
	s_addc_u32 s9, s9, 0
	global_load_dword v185, v3, s[8:9]
	s_add_u32 s8, s8, 0x6000
	s_addc_u32 s9, s9, 0
	global_load_dword v186, v3, s[8:9]
	s_add_u32 s8, s8, 0x6000
	s_addc_u32 s9, s9, 0
	global_load_dword v187, v3, s[8:9]
	s_add_u32 s8, s8, 0x6000
	s_addc_u32 s9, s9, 0
	global_load_dword v192, v3, s[8:9]
	s_add_u32 s8, s8, 0x6000
	s_addc_u32 s9, s9, 0
	global_load_dword v193, v3, s[8:9]
	s_add_u32 s8, s8, 0x6000
	s_addc_u32 s9, s9, 0
	global_load_dword v194, v3, s[8:9]
	s_add_u32 s8, s8, 0x6000
	s_addc_u32 s9, s9, 0
	global_load_dword v195, v3, s[8:9]
	s_add_u32 s8, s8, 0x6000
	s_addc_u32 s9, s9, 0
	global_load_dword v196, v3, s[8:9]
	s_add_u32 s8, s8, 0x6000
	s_addc_u32 s9, s9, 0
	global_load_dword v197, v3, s[8:9]
	s_add_u32 s8, s8, 0x6000
	s_addc_u32 s9, s9, 0
	global_load_dword v198, v3, s[8:9]
	s_add_u32 s8, s8, 0x6000
	s_addc_u32 s9, s9, 0
	global_load_dword v199, v3, s[8:9]
	s_add_u32 s8, s8, 0x6000
	s_addc_u32 s9, s9, 0
	v_lshlrev_b32_e32 v23, 8, v10
	s_waitcnt lgkmcnt(0)
	s_barrier
	ds_read_b128 v[28:31], v23
	ds_read_b128 v[32:35], v23 offset:4096
	ds_read_b128 v[36:39], v23 offset:8192
	ds_read_b128 v[40:43], v23 offset:12288
	ds_read_b128 v[44:47], v23 offset:16384
	ds_read_b128 v[74:77], v23 offset:16
	ds_read_b128 v[78:81], v23 offset:4112
	ds_read_b128 v[82:85], v23 offset:8208
	ds_read_b128 v[86:89], v23 offset:12304
	ds_read_b128 v[90:93], v23 offset:16400
	s_waitcnt vmcnt(60) lgkmcnt(5)
	v_mul_f32_e32 v4, v28, v132
	v_mul_f32_e32 v5, v32, v132
	v_mul_f32_e32 v12, v36, v132
	v_mul_f32_e32 v13, v40, v132
	v_mul_f32_e32 v22, v44, v132
	v_fmac_f32_e32 v4, v29, v133
	v_fmac_f32_e32 v5, v33, v133
	v_fmac_f32_e32 v12, v37, v133
	v_fmac_f32_e32 v13, v41, v133
	v_fmac_f32_e32 v22, v45, v133
	v_fmac_f32_e32 v4, v30, v134
	v_fmac_f32_e32 v5, v34, v134
	v_fmac_f32_e32 v12, v38, v134
	v_fmac_f32_e32 v13, v42, v134
	v_fmac_f32_e32 v22, v46, v134
	v_fmac_f32_e32 v4, v31, v135
	v_fmac_f32_e32 v5, v35, v135
	v_fmac_f32_e32 v12, v39, v135
	v_fmac_f32_e32 v13, v43, v135
	v_fmac_f32_e32 v22, v47, v135
	ds_read_b128 v[28:31], v23 offset:32
	ds_read_b128 v[32:35], v23 offset:4128
	ds_read_b128 v[36:39], v23 offset:8224
	ds_read_b128 v[40:43], v23 offset:12320
	ds_read_b128 v[44:47], v23 offset:16416
	s_waitcnt vmcnt(56) lgkmcnt(5)
	v_fmac_f32_e32 v4, v74, v136
	v_fmac_f32_e32 v5, v78, v136
	v_fmac_f32_e32 v12, v82, v136
	v_fmac_f32_e32 v13, v86, v136
	v_fmac_f32_e32 v22, v90, v136
	v_fmac_f32_e32 v4, v75, v137
	v_fmac_f32_e32 v5, v79, v137
	v_fmac_f32_e32 v12, v83, v137
	v_fmac_f32_e32 v13, v87, v137
	v_fmac_f32_e32 v22, v91, v137
	v_fmac_f32_e32 v4, v76, v138
	v_fmac_f32_e32 v5, v80, v138
	v_fmac_f32_e32 v12, v84, v138
	v_fmac_f32_e32 v13, v88, v138
	v_fmac_f32_e32 v22, v92, v138
	v_fmac_f32_e32 v4, v77, v139
	v_fmac_f32_e32 v5, v81, v139
	v_fmac_f32_e32 v12, v85, v139
	v_fmac_f32_e32 v13, v89, v139
	v_fmac_f32_e32 v22, v93, v139
	ds_read_b128 v[74:77], v23 offset:48
	ds_read_b128 v[78:81], v23 offset:4144
	ds_read_b128 v[82:85], v23 offset:8240
	ds_read_b128 v[86:89], v23 offset:12336
	ds_read_b128 v[90:93], v23 offset:16432
	s_waitcnt vmcnt(52) lgkmcnt(5)
	v_fmac_f32_e32 v4, v28, v140
	v_fmac_f32_e32 v5, v32, v140
	v_fmac_f32_e32 v12, v36, v140
	v_fmac_f32_e32 v13, v40, v140
	v_fmac_f32_e32 v22, v44, v140
	v_fmac_f32_e32 v4, v29, v141
	v_fmac_f32_e32 v5, v33, v141
	v_fmac_f32_e32 v12, v37, v141
	v_fmac_f32_e32 v13, v41, v141
	v_fmac_f32_e32 v22, v45, v141
	v_fmac_f32_e32 v4, v30, v142
	v_fmac_f32_e32 v5, v34, v142
	v_fmac_f32_e32 v12, v38, v142
	v_fmac_f32_e32 v13, v42, v142
	v_fmac_f32_e32 v22, v46, v142
	v_fmac_f32_e32 v4, v31, v143
	v_fmac_f32_e32 v5, v35, v143
	v_fmac_f32_e32 v12, v39, v143
	v_fmac_f32_e32 v13, v43, v143
	v_fmac_f32_e32 v22, v47, v143
	ds_read_b128 v[28:31], v23 offset:64
	ds_read_b128 v[32:35], v23 offset:4160
	ds_read_b128 v[36:39], v23 offset:8256
	ds_read_b128 v[40:43], v23 offset:12352
	ds_read_b128 v[44:47], v23 offset:16448
	s_waitcnt vmcnt(48) lgkmcnt(5)
	v_fmac_f32_e32 v4, v74, v144
	v_fmac_f32_e32 v5, v78, v144
	v_fmac_f32_e32 v12, v82, v144
	v_fmac_f32_e32 v13, v86, v144
	v_fmac_f32_e32 v22, v90, v144
	v_fmac_f32_e32 v4, v75, v145
	v_fmac_f32_e32 v5, v79, v145
	v_fmac_f32_e32 v12, v83, v145
	v_fmac_f32_e32 v13, v87, v145
	v_fmac_f32_e32 v22, v91, v145
	v_fmac_f32_e32 v4, v76, v146
	v_fmac_f32_e32 v5, v80, v146
	v_fmac_f32_e32 v12, v84, v146
	v_fmac_f32_e32 v13, v88, v146
	v_fmac_f32_e32 v22, v92, v146
	v_fmac_f32_e32 v4, v77, v147
	v_fmac_f32_e32 v5, v81, v147
	v_fmac_f32_e32 v12, v85, v147
	v_fmac_f32_e32 v13, v89, v147
	v_fmac_f32_e32 v22, v93, v147
	ds_read_b128 v[74:77], v23 offset:80
	ds_read_b128 v[78:81], v23 offset:4176
	ds_read_b128 v[82:85], v23 offset:8272
	ds_read_b128 v[86:89], v23 offset:12368
	ds_read_b128 v[90:93], v23 offset:16464
	s_waitcnt vmcnt(44) lgkmcnt(5)
	v_fmac_f32_e32 v4, v28, v148
	v_fmac_f32_e32 v5, v32, v148
	v_fmac_f32_e32 v12, v36, v148
	v_fmac_f32_e32 v13, v40, v148
	v_fmac_f32_e32 v22, v44, v148
	v_fmac_f32_e32 v4, v29, v149
	v_fmac_f32_e32 v5, v33, v149
	v_fmac_f32_e32 v12, v37, v149
	v_fmac_f32_e32 v13, v41, v149
	v_fmac_f32_e32 v22, v45, v149
	v_fmac_f32_e32 v4, v30, v150
	v_fmac_f32_e32 v5, v34, v150
	v_fmac_f32_e32 v12, v38, v150
	v_fmac_f32_e32 v13, v42, v150
	v_fmac_f32_e32 v22, v46, v150
	v_fmac_f32_e32 v4, v31, v151
	v_fmac_f32_e32 v5, v35, v151
	v_fmac_f32_e32 v12, v39, v151
	v_fmac_f32_e32 v13, v43, v151
	v_fmac_f32_e32 v22, v47, v151
	ds_read_b128 v[28:31], v23 offset:96
	ds_read_b128 v[32:35], v23 offset:4192
	ds_read_b128 v[36:39], v23 offset:8288
	ds_read_b128 v[40:43], v23 offset:12384
	ds_read_b128 v[44:47], v23 offset:16480
	s_waitcnt vmcnt(40) lgkmcnt(5)
	v_fmac_f32_e32 v4, v74, v152
	v_fmac_f32_e32 v5, v78, v152
	v_fmac_f32_e32 v12, v82, v152
	v_fmac_f32_e32 v13, v86, v152
	v_fmac_f32_e32 v22, v90, v152
	v_fmac_f32_e32 v4, v75, v153
	v_fmac_f32_e32 v5, v79, v153
	v_fmac_f32_e32 v12, v83, v153
	v_fmac_f32_e32 v13, v87, v153
	v_fmac_f32_e32 v22, v91, v153
	v_fmac_f32_e32 v4, v76, v154
	v_fmac_f32_e32 v5, v80, v154
	v_fmac_f32_e32 v12, v84, v154
	v_fmac_f32_e32 v13, v88, v154
	v_fmac_f32_e32 v22, v92, v154
	v_fmac_f32_e32 v4, v77, v155
	v_fmac_f32_e32 v5, v81, v155
	v_fmac_f32_e32 v12, v85, v155
	v_fmac_f32_e32 v13, v89, v155
	v_fmac_f32_e32 v22, v93, v155
	ds_read_b128 v[74:77], v23 offset:112
	ds_read_b128 v[78:81], v23 offset:4208
	ds_read_b128 v[82:85], v23 offset:8304
	ds_read_b128 v[86:89], v23 offset:12400
	ds_read_b128 v[90:93], v23 offset:16496
	s_waitcnt vmcnt(36) lgkmcnt(5)
	v_fmac_f32_e32 v4, v28, v156
	v_fmac_f32_e32 v5, v32, v156
	v_fmac_f32_e32 v12, v36, v156
	v_fmac_f32_e32 v13, v40, v156
	v_fmac_f32_e32 v22, v44, v156
	v_fmac_f32_e32 v4, v29, v157
	v_fmac_f32_e32 v5, v33, v157
	v_fmac_f32_e32 v12, v37, v157
	v_fmac_f32_e32 v13, v41, v157
	v_fmac_f32_e32 v22, v45, v157
	v_fmac_f32_e32 v4, v30, v158
	v_fmac_f32_e32 v5, v34, v158
	v_fmac_f32_e32 v12, v38, v158
	v_fmac_f32_e32 v13, v42, v158
	v_fmac_f32_e32 v22, v46, v158
	v_fmac_f32_e32 v4, v31, v159
	v_fmac_f32_e32 v5, v35, v159
	v_fmac_f32_e32 v12, v39, v159
	v_fmac_f32_e32 v13, v43, v159
	v_fmac_f32_e32 v22, v47, v159
	ds_read_b128 v[28:31], v23 offset:128
	ds_read_b128 v[32:35], v23 offset:4224
	ds_read_b128 v[36:39], v23 offset:8320
	ds_read_b128 v[40:43], v23 offset:12416
	ds_read_b128 v[44:47], v23 offset:16512
	s_waitcnt vmcnt(32) lgkmcnt(5)
	v_fmac_f32_e32 v4, v74, v160
	v_fmac_f32_e32 v5, v78, v160
	v_fmac_f32_e32 v12, v82, v160
	v_fmac_f32_e32 v13, v86, v160
	v_fmac_f32_e32 v22, v90, v160
	v_fmac_f32_e32 v4, v75, v161
	v_fmac_f32_e32 v5, v79, v161
	v_fmac_f32_e32 v12, v83, v161
	v_fmac_f32_e32 v13, v87, v161
	v_fmac_f32_e32 v22, v91, v161
	v_fmac_f32_e32 v4, v76, v162
	v_fmac_f32_e32 v5, v80, v162
	v_fmac_f32_e32 v12, v84, v162
	v_fmac_f32_e32 v13, v88, v162
	v_fmac_f32_e32 v22, v92, v162
	v_fmac_f32_e32 v4, v77, v163
	v_fmac_f32_e32 v5, v81, v163
	v_fmac_f32_e32 v12, v85, v163
	v_fmac_f32_e32 v13, v89, v163
	v_fmac_f32_e32 v22, v93, v163
	ds_read_b128 v[74:77], v23 offset:144
	ds_read_b128 v[78:81], v23 offset:4240
	ds_read_b128 v[82:85], v23 offset:8336
	ds_read_b128 v[86:89], v23 offset:12432
	ds_read_b128 v[90:93], v23 offset:16528
	s_waitcnt vmcnt(28) lgkmcnt(5)
	v_fmac_f32_e32 v4, v28, v164
	v_fmac_f32_e32 v5, v32, v164
	v_fmac_f32_e32 v12, v36, v164
	v_fmac_f32_e32 v13, v40, v164
	v_fmac_f32_e32 v22, v44, v164
	v_fmac_f32_e32 v4, v29, v165
	v_fmac_f32_e32 v5, v33, v165
	v_fmac_f32_e32 v12, v37, v165
	v_fmac_f32_e32 v13, v41, v165
	v_fmac_f32_e32 v22, v45, v165
	v_fmac_f32_e32 v4, v30, v166
	v_fmac_f32_e32 v5, v34, v166
	v_fmac_f32_e32 v12, v38, v166
	v_fmac_f32_e32 v13, v42, v166
	v_fmac_f32_e32 v22, v46, v166
	v_fmac_f32_e32 v4, v31, v167
	v_fmac_f32_e32 v5, v35, v167
	v_fmac_f32_e32 v12, v39, v167
	v_fmac_f32_e32 v13, v43, v167
	v_fmac_f32_e32 v22, v47, v167
	ds_read_b128 v[28:31], v23 offset:160
	ds_read_b128 v[32:35], v23 offset:4256
	ds_read_b128 v[36:39], v23 offset:8352
	ds_read_b128 v[40:43], v23 offset:12448
	ds_read_b128 v[44:47], v23 offset:16544
	s_waitcnt vmcnt(24) lgkmcnt(5)
	v_fmac_f32_e32 v4, v74, v168
	v_fmac_f32_e32 v5, v78, v168
	v_fmac_f32_e32 v12, v82, v168
	v_fmac_f32_e32 v13, v86, v168
	v_fmac_f32_e32 v22, v90, v168
	v_fmac_f32_e32 v4, v75, v169
	v_fmac_f32_e32 v5, v79, v169
	v_fmac_f32_e32 v12, v83, v169
	v_fmac_f32_e32 v13, v87, v169
	v_fmac_f32_e32 v22, v91, v169
	v_fmac_f32_e32 v4, v76, v170
	v_fmac_f32_e32 v5, v80, v170
	v_fmac_f32_e32 v12, v84, v170
	v_fmac_f32_e32 v13, v88, v170
	v_fmac_f32_e32 v22, v92, v170
	v_fmac_f32_e32 v4, v77, v171
	v_fmac_f32_e32 v5, v81, v171
	v_fmac_f32_e32 v12, v85, v171
	v_fmac_f32_e32 v13, v89, v171
	v_fmac_f32_e32 v22, v93, v171
	ds_read_b128 v[74:77], v23 offset:176
	ds_read_b128 v[78:81], v23 offset:4272
	ds_read_b128 v[82:85], v23 offset:8368
	ds_read_b128 v[86:89], v23 offset:12464
	ds_read_b128 v[90:93], v23 offset:16560
	s_waitcnt vmcnt(20) lgkmcnt(5)
	v_fmac_f32_e32 v4, v28, v172
	v_fmac_f32_e32 v5, v32, v172
	v_fmac_f32_e32 v12, v36, v172
	v_fmac_f32_e32 v13, v40, v172
	v_fmac_f32_e32 v22, v44, v172
	v_fmac_f32_e32 v4, v29, v173
	v_fmac_f32_e32 v5, v33, v173
	v_fmac_f32_e32 v12, v37, v173
	v_fmac_f32_e32 v13, v41, v173
	v_fmac_f32_e32 v22, v45, v173
	v_fmac_f32_e32 v4, v30, v174
	v_fmac_f32_e32 v5, v34, v174
	v_fmac_f32_e32 v12, v38, v174
	v_fmac_f32_e32 v13, v42, v174
	v_fmac_f32_e32 v22, v46, v174
	v_fmac_f32_e32 v4, v31, v175
	v_fmac_f32_e32 v5, v35, v175
	v_fmac_f32_e32 v12, v39, v175
	v_fmac_f32_e32 v13, v43, v175
	v_fmac_f32_e32 v22, v47, v175
	ds_read_b128 v[28:31], v23 offset:192
	ds_read_b128 v[32:35], v23 offset:4288
	ds_read_b128 v[36:39], v23 offset:8384
	ds_read_b128 v[40:43], v23 offset:12480
	ds_read_b128 v[44:47], v23 offset:16576
	s_waitcnt vmcnt(16) lgkmcnt(5)
	v_fmac_f32_e32 v4, v74, v176
	v_fmac_f32_e32 v5, v78, v176
	v_fmac_f32_e32 v12, v82, v176
	v_fmac_f32_e32 v13, v86, v176
	v_fmac_f32_e32 v22, v90, v176
	v_fmac_f32_e32 v4, v75, v177
	v_fmac_f32_e32 v5, v79, v177
	v_fmac_f32_e32 v12, v83, v177
	v_fmac_f32_e32 v13, v87, v177
	v_fmac_f32_e32 v22, v91, v177
	v_fmac_f32_e32 v4, v76, v178
	v_fmac_f32_e32 v5, v80, v178
	v_fmac_f32_e32 v12, v84, v178
	v_fmac_f32_e32 v13, v88, v178
	v_fmac_f32_e32 v22, v92, v178
	v_fmac_f32_e32 v4, v77, v179
	v_fmac_f32_e32 v5, v81, v179
	v_fmac_f32_e32 v12, v85, v179
	v_fmac_f32_e32 v13, v89, v179
	v_fmac_f32_e32 v22, v93, v179
	ds_read_b128 v[74:77], v23 offset:208
	ds_read_b128 v[78:81], v23 offset:4304
	ds_read_b128 v[82:85], v23 offset:8400
	ds_read_b128 v[86:89], v23 offset:12496
	ds_read_b128 v[90:93], v23 offset:16592
	s_waitcnt vmcnt(12) lgkmcnt(5)
	v_fmac_f32_e32 v4, v28, v180
	v_fmac_f32_e32 v5, v32, v180
	v_fmac_f32_e32 v12, v36, v180
	v_fmac_f32_e32 v13, v40, v180
	v_fmac_f32_e32 v22, v44, v180
	v_fmac_f32_e32 v4, v29, v181
	v_fmac_f32_e32 v5, v33, v181
	v_fmac_f32_e32 v12, v37, v181
	v_fmac_f32_e32 v13, v41, v181
	v_fmac_f32_e32 v22, v45, v181
	v_fmac_f32_e32 v4, v30, v182
	v_fmac_f32_e32 v5, v34, v182
	v_fmac_f32_e32 v12, v38, v182
	v_fmac_f32_e32 v13, v42, v182
	v_fmac_f32_e32 v22, v46, v182
	v_fmac_f32_e32 v4, v31, v183
	v_fmac_f32_e32 v5, v35, v183
	v_fmac_f32_e32 v12, v39, v183
	v_fmac_f32_e32 v13, v43, v183
	v_fmac_f32_e32 v22, v47, v183
	ds_read_b128 v[28:31], v23 offset:224
	ds_read_b128 v[32:35], v23 offset:4320
	ds_read_b128 v[36:39], v23 offset:8416
	ds_read_b128 v[40:43], v23 offset:12512
	ds_read_b128 v[44:47], v23 offset:16608
	s_waitcnt vmcnt(8) lgkmcnt(5)
	v_fmac_f32_e32 v4, v74, v184
	v_fmac_f32_e32 v5, v78, v184
	v_fmac_f32_e32 v12, v82, v184
	v_fmac_f32_e32 v13, v86, v184
	v_fmac_f32_e32 v22, v90, v184
	v_fmac_f32_e32 v4, v75, v185
	v_fmac_f32_e32 v5, v79, v185
	v_fmac_f32_e32 v12, v83, v185
	v_fmac_f32_e32 v13, v87, v185
	v_fmac_f32_e32 v22, v91, v185
	v_fmac_f32_e32 v4, v76, v186
	v_fmac_f32_e32 v5, v80, v186
	v_fmac_f32_e32 v12, v84, v186
	v_fmac_f32_e32 v13, v88, v186
	v_fmac_f32_e32 v22, v92, v186
	v_fmac_f32_e32 v4, v77, v187
	v_fmac_f32_e32 v5, v81, v187
	v_fmac_f32_e32 v12, v85, v187
	v_fmac_f32_e32 v13, v89, v187
	v_fmac_f32_e32 v22, v93, v187
	ds_read_b128 v[74:77], v23 offset:240
	ds_read_b128 v[78:81], v23 offset:4336
	ds_read_b128 v[82:85], v23 offset:8432
	ds_read_b128 v[86:89], v23 offset:12528
	ds_read_b128 v[90:93], v23 offset:16624
	s_waitcnt vmcnt(4) lgkmcnt(5)
	v_fmac_f32_e32 v4, v28, v192
	v_fmac_f32_e32 v5, v32, v192
	v_fmac_f32_e32 v12, v36, v192
	v_fmac_f32_e32 v13, v40, v192
	v_fmac_f32_e32 v22, v44, v192
	v_fmac_f32_e32 v4, v29, v193
	v_fmac_f32_e32 v5, v33, v193
	v_fmac_f32_e32 v12, v37, v193
	v_fmac_f32_e32 v13, v41, v193
	v_fmac_f32_e32 v22, v45, v193
	v_fmac_f32_e32 v4, v30, v194
	v_fmac_f32_e32 v5, v34, v194
	v_fmac_f32_e32 v12, v38, v194
	v_fmac_f32_e32 v13, v42, v194
	v_fmac_f32_e32 v22, v46, v194
	v_fmac_f32_e32 v4, v31, v195
	v_fmac_f32_e32 v5, v35, v195
	v_fmac_f32_e32 v12, v39, v195
	v_fmac_f32_e32 v13, v43, v195
	v_fmac_f32_e32 v22, v47, v195
	s_waitcnt vmcnt(0) lgkmcnt(0)
	v_fmac_f32_e32 v4, v74, v196
	v_fmac_f32_e32 v5, v78, v196
	v_fmac_f32_e32 v12, v82, v196
	v_fmac_f32_e32 v13, v86, v196
	v_fmac_f32_e32 v22, v90, v196
	v_fmac_f32_e32 v4, v75, v197
	v_fmac_f32_e32 v5, v79, v197
	v_fmac_f32_e32 v12, v83, v197
	v_fmac_f32_e32 v13, v87, v197
	v_fmac_f32_e32 v22, v91, v197
	v_fmac_f32_e32 v4, v76, v198
	v_fmac_f32_e32 v5, v80, v198
	v_fmac_f32_e32 v12, v84, v198
	v_fmac_f32_e32 v13, v88, v198
	v_fmac_f32_e32 v22, v92, v198
	v_fmac_f32_e32 v4, v77, v199
	v_fmac_f32_e32 v5, v81, v199
	v_fmac_f32_e32 v12, v85, v199
	v_fmac_f32_e32 v13, v89, v199
	v_fmac_f32_e32 v22, v93, v199
	v_mov_b32_e32 v2, v11
	v_mad_u64_u32 v[2:3], s[6:7], v0, 20, v[2:3]
	v_add_u32_e32 v3, 0x5000, v2
	s_movk_i32 s6, 0xa0
	ds_write2_b32 v3, v4, v5 offset1:1
	v_add_u32_e32 v3, 0x5008, v2
	v_cmp_gt_i32_e32 vcc, s6, v0
	ds_write2_b32 v3, v12, v13 offset1:1
	ds_write_b32 v2, v22 offset:20496
	s_waitcnt lgkmcnt(0)
	s_barrier
	s_and_saveexec_b64 s[6:7], vcc
	s_cbranch_execz .LBB0_23
	s_lshl_b32 s8, s39, 5
	v_or_b32_e32 v2, s8, v1
	v_ashrrev_i32_e32 v3, 31, v2
	v_lshl_add_u64 v[2:3], v[2:3], 2, s[50:51]
	global_load_dword v21, v[2:3], off
	v_lshlrev_b32_e32 v0, 2, v10
	v_mul_u32_u24_e32 v2, 20, v1
	s_movk_i32 s9, 0x1800
	v_mul_lo_u32 v3, v10, s9
	v_add3_u32 v0, 0, v0, v2
	v_add_u32_e32 v2, s8, v3
	v_add_u32_e32 v3, 0x5000, v0
	v_add_u32_e32 v4, 0x5400, v0
	v_add_u32_e32 v22, 0x5e00, v0
	v_add_u32_e32 v28, 0x6400, v0
	v_add_u32_e32 v30, 0x6800, v0
	v_add_u32_e32 v32, 0x6e00, v0
	v_add_u32_e32 v34, 0x7200, v0
	v_add_u32_e32 v10, 0x5a00, v0
	v_or_b32_e32 v0, v2, v1
	ds_read2_b32 v[2:3], v3 offset1:160
	ds_read2_b32 v[4:5], v4 offset0:64 offset1:224
	ds_read2_b32 v[12:13], v10 offset1:160
	ds_read2_b32 v[22:23], v22 offset0:64 offset1:224
	ds_read2_b32 v[28:29], v28 offset1:160
	ds_read2_b32 v[30:31], v30 offset0:64 offset1:224
	ds_read2_b32 v[32:33], v32 offset1:160
	ds_read2_b32 v[34:35], v34 offset0:64 offset1:224
	v_ashrrev_i32_e32 v1, 31, v0
	v_lshl_add_u64 v[0:1], v[0:1], 2, s[14:15]
	s_waitcnt vmcnt(0) lgkmcnt(7)
	v_add_f32_e32 v2, v21, v2
	v_add_f32_e32 v2, v2, v3
	s_waitcnt lgkmcnt(6)
	v_add_f32_e32 v2, v2, v4
	v_add_f32_e32 v2, v2, v5
	s_waitcnt lgkmcnt(5)
	v_add_f32_e32 v2, v2, v12
	v_add_f32_e32 v2, v2, v13
	s_waitcnt lgkmcnt(4)
	v_add_f32_e32 v2, v2, v22
	v_add_f32_e32 v2, v2, v23
	s_waitcnt lgkmcnt(3)
	v_add_f32_e32 v2, v2, v28
	v_add_f32_e32 v2, v2, v29
	s_waitcnt lgkmcnt(2)
	v_add_f32_e32 v2, v2, v30
	v_add_f32_e32 v2, v2, v31
	s_waitcnt lgkmcnt(1)
	v_add_f32_e32 v2, v2, v32
	v_add_f32_e32 v2, v2, v33
	s_waitcnt lgkmcnt(0)
	v_add_f32_e32 v2, v2, v34
	v_add_f32_e32 v2, v2, v35
	global_store_dword v[0:1], v2, off
	s_branch .LBB0_23
